# added: FoX forget-gate cumsum spread one sequence per CU (was 8 per CU on 16 CUs)
# baseline (speedup 1.0000x reference)
.LBB0_287:
	s_or_b64 exec, exec, s[8:9]
	v_cndmask_b32_e64 v0, 0, 1, s[4:5]
	v_cmp_ne_u32_e64 s[2:3], 1, v0
	s_andn2_b64 vcc, exec, s[4:5]
	s_waitcnt lgkmcnt(0)
	v_writelane_b32 v255, s2, 13
	s_barrier
	s_nop 0
	v_writelane_b32 v255, s3, 14
	s_cbranch_vccnz .LBB0_352
	s_mov_b32 s3, 0
	s_mov_b32 s0, s1
	v_mov_b32_e32 v0, v195
	v_readlane_b32 s4, v252, 38
	v_and_b32_e32 v36, 63, v0
	v_mov_b32_e32 v0, v195
	v_cmp_eq_u32_e64 s[40:41], 0, v36
	v_readfirstlane_b32 s2, v0
	s_ashr_i32 s2, s2, 6
	s_add_i32 s14, s2, s4
	s_lshr_b32 s100, s4, 3
	s_cmp_eq_u32 s2, 0
	s_cselect_b32 s100, s100, 0xff
	s_cmpk_gt_i32 s100, 0x7f
	s_cbranch_scc1 .LBB0_291
	s_ashr_i32 s8, s0, 31
	s_ashr_i32 s5, s3, 31
	v_readlane_b32 s4, v252, 53
	s_add_u32 s4, s4, s3
	v_readlane_b32 s3, v252, 54
	s_addc_u32 s5, s3, s5
	v_lshlrev_b32_e32 v0, 8, v36
	v_lshl_add_u64 v[6:7], s[4:5], 0, v[0:1]
	v_and_b32_e32 v0, 64, v200
	v_add_u32_e32 v2, -1, v200
	v_cmp_lt_i32_e32 vcc, v2, v0
	s_ashr_i32 s3, s2, 31
	v_readlane_b32 s4, v252, 38
	s_lshr_b32 s4, s4, 3
	v_cndmask_b32_e32 v2, v2, v200, vcc
	v_lshlrev_b32_e32 v37, 2, v2
	v_add_u32_e32 v2, -2, v200
	v_cmp_lt_i32_e32 vcc, v2, v0
	s_add_u32 s2, s4, s2
	v_readlane_b32 s4, v254, 34
	v_cndmask_b32_e32 v2, v2, v200, vcc
	v_lshlrev_b32_e32 v38, 2, v2
	v_add_u32_e32 v2, -4, v200
	v_cmp_lt_i32_e32 vcc, v2, v0
	s_addc_u32 s3, s4, s3
	s_lshl_b64 s[2:3], s[2:3], 14
	v_cndmask_b32_e32 v2, v2, v200, vcc
	v_lshlrev_b32_e32 v39, 2, v2
	v_add_u32_e32 v2, -8, v200
	v_cmp_lt_i32_e32 vcc, v2, v0
	v_readlane_b32 s4, v254, 32
	s_add_u32 s0, s4, s0
	v_cndmask_b32_e32 v2, v2, v200, vcc
	v_lshlrev_b32_e32 v40, 2, v2
	v_add_u32_e32 v2, -16, v200
	v_cmp_lt_i32_e32 vcc, v2, v0
	v_readlane_b32 s4, v254, 33
	s_addc_u32 s4, s4, s8
	v_cndmask_b32_e32 v2, v2, v200, vcc
	v_lshlrev_b32_e32 v41, 2, v2
	v_subrev_u32_e32 v2, 32, v200
	v_cmp_lt_i32_e32 vcc, v2, v0
	s_add_u32 s2, s0, s2
	s_addc_u32 s3, s4, s3
	v_cndmask_b32_e32 v0, v2, v200, vcc
	v_lshlrev_b32_e32 v42, 2, v0
	v_lshlrev_b32_e32 v0, 4, v36
	v_cmp_gt_u32_e64 s[42:43], 2, v36
	v_cmp_gt_u32_e64 s[44:45], 4, v36
	v_cmp_gt_u32_e64 s[46:47], 8, v36
	v_cmp_gt_u32_e64 s[48:49], 16, v36
	v_cmp_gt_u32_e64 s[50:51], 32, v36
	v_lshl_add_u64 v[8:9], s[2:3], 0, v[0:1]
	s_mov_b32 s4, s100
